# v13 + phase 0 cache_a k/v conversion loop: both loads of an iteration issued before the first wait
# baseline (speedup 1.0000x reference)
.LBB0_1281:
	v_lshl_add_u64 v[10:11], s[80:81], 0, v[8:9]
	global_load_dword v10, v[10:11], off
	v_lshl_add_u64 v[62:63], s[82:83], 0, v[8:9]
	global_load_dword v62, v[62:63], off
	s_movk_i32 s3, 0x1200
	v_bfe_u32 v0, v5, 7, 9
	s_waitcnt vmcnt(1)
	v_cvt_pk_bf16_f32 v12, v10, s0
	v_mul_i32_i24_sdwa v10, sext(v5), s3 dst_sel:DWORD dst_unused:UNUSED_PAD src0_sel:WORD_1 src1_sel:DWORD
	v_or_b32_e32 v10, v10, v0
	v_add_u32_e32 v10, 0x2000, v10
	v_ashrrev_i32_e32 v11, 31, v10
	v_lshlrev_b64 v[10:11], 8, v[10:11]
	v_lshl_add_u64 v[10:11], v[6:7], 0, v[10:11]
	global_store_short v[10:11], v12, off
	s_mov_b32 s3, 0x3ffff
	v_lshlrev_b32_e32 v0, 1, v0
	v_lshl_add_u64 v[8:9], v[8:9], 0, s[6:7]
	s_waitcnt vmcnt(1)
	v_cvt_pk_bf16_f32 v12, v62, s0
	v_lshlrev_b32_sdwa v10, v231, sext(v5) dst_sel:DWORD dst_unused:UNUSED_PAD src0_sel:DWORD src1_sel:WORD_1
	v_or3_b32 v10, v10, v3, v4
	v_mul_hi_i32_i24_e32 v11, 0x2400, v10
	v_mul_i32_i24_e32 v10, 0x2400, v10
	v_add_u32_e32 v5, s10, v5
	v_lshl_add_u64 v[10:11], s[4:5], 0, v[10:11]
	v_cmp_lt_i32_e32 vcc, s3, v5
	v_lshl_add_u64 v[10:11], v[10:11], 0, v[0:1]
	s_or_b64 s[8:9], vcc, s[8:9]
	global_store_short v[10:11], v12, off
	s_andn2_b64 exec, exec, s[8:9]
	s_cbranch_execnz .LBB0_1281
